# grid-barrier seams 2-9: the acquire-side buffer_inv sc1 issued right behind the arrival atomic (all waves of the workgroup are parked and the polls bypass L1, so nothing refills it) - its latency runs
# speedup vs baseline: 1.0127x; 1.0127x over previous
; __device__ __forceinline__ int lane_id_asm() { int l; asm volatile("v_mbcnt_lo_u32_b32 %0, -1, 0\n\tv_mbcnt_hi_u32_b32 %0, -1, %0" : "=v"(l)); return l; }
; __device__ __forceinline__ unsigned xb_ld(unsigned* p)              { return __hip_atomic_load(p, __ATOMIC_RELAXED, __HIP_MEMORY_SCOPE_AGENT); }
; __device__ __forceinline__ unsigned xb_add(unsigned* p, unsigned v) { return __hip_atomic_fetch_add(p, v, __ATOMIC_RELAXED, __HIP_MEMORY_SCOPE_AGENT); }
; #define XB_SPIN(cond, bar) do { unsigned _sp = 0; while (cond) { __builtin_amdgcn_s_sleep(1); \
;     if ((++_sp & 255u) == 0u) { if (xb_ld(&(bar)[XB_TMO])) break; if (_sp > XB_SPIN_CAP) { atomicAdd(&(bar)[XB_TMO], 1u); break; } } } } while (0)
; __device__ __forceinline__ void xcd_barrier(const XcdBarrier& b, const int wid) {
;     asm volatile("s_waitcnt vmcnt(0)" ::: "memory");
;     __syncthreads();
;     if (wid == 0 && lane_id_asm() == 0) {
;         unsigned* bar = b.bar;
;         __builtin_amdgcn_s_waitcnt(0);
;         unsigned nloc = b.st[0], nx = b.st[1];
;         if (nloc == 0u) { xcd_barrier_complete(bar, b.x, nloc, nx); b.st[0] = nloc; b.st[1] = nx; }
;         const unsigned old = xb_add(&bar[XB_XSUB(b.x)], 1u);
;         const unsigned gen = old / nloc;
;         if (old + 1u == (gen + 1u) * nloc) {
;             __builtin_amdgcn_fence(__ATOMIC_RELEASE, "agent");
;             asm volatile("s_waitcnt vmcnt(0)" ::: "memory");
;             const unsigned og = xb_add(&bar[XB_TOP], 1u);
;             const unsigned tg = og / nx;
;             if (og + 1u == (tg + 1u) * nx) xb_add(&bar[XB_TOPGEN], 1u);
;             else XB_SPIN(xb_ld(&bar[XB_TOPGEN]) == tg, bar);
.LBB0_686:
	v_readlane_b32 s0, v254, 13
	v_readlane_b32 s1, v254, 14
	s_and_b64 vcc, exec, s[0:1]
	s_cbranch_vccnz .LBB0_738
	s_waitcnt vmcnt(0)
	s_cmp_gt_u32 s79, 63
	s_waitcnt vmcnt(0) lgkmcnt(0)
	s_barrier
	s_cbranch_scc1 .LBB0_737
	v_mbcnt_lo_u32_b32 v0, -1, 0
	v_mbcnt_hi_u32_b32 v0, -1, v0
	s_nop 0
	v_cmp_eq_u32_e32 vcc, 0, v0
	s_and_saveexec_b64 s[0:1], vcc
	s_cbranch_execz .LBB0_736
	v_readlane_b32 s2, v254, 9
	s_waitcnt vmcnt(0) expcnt(0) lgkmcnt(0)
	s_nop 0
	v_mov_b32_e32 v0, s2
	ds_read_b32 v2, v0
	ds_read_b32 v3, v0 offset:4
	ds_read_b32 v4, v0 offset:8
	ds_read_b32 v5, v0 offset:12
	v_readlane_b32 s2, v254, 8
	s_lshl_b32 s2, s2, 8
	v_readlane_b32 s4, v254, 6
	v_readlane_b32 s5, v254, 7
	s_add_u32 s2, s4, s2
	s_addc_u32 s3, s5, 0
	v_mov_b32_e32 v1, 0x1000
	v_mov_b32_e32 v6, 1
	global_atomic_add v1, v6, s[2:3] offset:1024
	buffer_inv sc1
	s_waitcnt lgkmcnt(0)
	v_add_u32_e32 v6, 1, v4
	ds_write_b32 v0, v6 offset:8
	v_add_u32_e32 v4, 2, v4
	v_mul_lo_u32 v2, v2, v4
	v_mul_lo_u32 v3, v3, v4
	s_add_u32 s10, s86, 0x7400
	s_addc_u32 s11, s87, 0
	s_mov_b32 s4, 0x200000
	v_cmp_eq_u32_e32 vcc, 0, v5
	s_cbranch_vccnz .Lxb2_wait

; __device__ __forceinline__ unsigned xb_ld(unsigned* p)              { return __hip_atomic_load(p, __ATOMIC_RELAXED, __HIP_MEMORY_SCOPE_AGENT); }
; #define XB_SPIN(cond, bar) do { unsigned _sp = 0; while (cond) { __builtin_amdgcn_s_sleep(1); \
;     if ((++_sp & 255u) == 0u) { if (xb_ld(&(bar)[XB_TMO])) break; if (_sp > XB_SPIN_CAP) { atomicAdd(&(bar)[XB_TMO], 1u); break; } } } } while (0)
; __device__ __forceinline__ void xcd_barrier(const XcdBarrier& b, const int wid) {
;     ...
;             XB_SPIN(xb_ld(&bar[XB_XGEN(b.x)]) == gen, bar);
;             __builtin_amdgcn_fence(__ATOMIC_ACQUIRE, "agent");
;             asm volatile("s_waitcnt vmcnt(0)" ::: "memory");
.Lxb2_w:
	global_load_dword v6, v0, s[10:11] sc1
	s_sub_i32 s4, s4, 1
	s_waitcnt vmcnt(0)
	v_cmp_ge_u32_e32 vcc, v6, v3
	s_cbranch_vccnz .Lxb2_acq
	s_cmp_eq_u32 s4, 0
	s_cbranch_scc1 .Lxb2_acq
	s_sleep 1
	s_branch .Lxb2_w
.Lxb2_acq:
	s_waitcnt vmcnt(0)
.LBB0_736:
	s_or_b64 exec, exec, s[0:1]

; __device__ __forceinline__ int lane_id_asm() { int l; asm volatile("v_mbcnt_lo_u32_b32 %0, -1, 0\n\tv_mbcnt_hi_u32_b32 %0, -1, %0" : "=v"(l)); return l; }
; __device__ __forceinline__ unsigned xb_ld(unsigned* p)              { return __hip_atomic_load(p, __ATOMIC_RELAXED, __HIP_MEMORY_SCOPE_AGENT); }
; __device__ __forceinline__ unsigned xb_add(unsigned* p, unsigned v) { return __hip_atomic_fetch_add(p, v, __ATOMIC_RELAXED, __HIP_MEMORY_SCOPE_AGENT); }
; #define XB_SPIN(cond, bar) do { unsigned _sp = 0; while (cond) { __builtin_amdgcn_s_sleep(1); \
;     if ((++_sp & 255u) == 0u) { if (xb_ld(&(bar)[XB_TMO])) break; if (_sp > XB_SPIN_CAP) { atomicAdd(&(bar)[XB_TMO], 1u); break; } } } } while (0)
; __device__ __forceinline__ void xcd_barrier(const XcdBarrier& b, const int wid) {
;     asm volatile("s_waitcnt vmcnt(0)" ::: "memory");
;     __syncthreads();
;     if (wid == 0 && lane_id_asm() == 0) {
;         unsigned* bar = b.bar;
;         __builtin_amdgcn_s_waitcnt(0);
;         unsigned nloc = b.st[0], nx = b.st[1];
;         if (nloc == 0u) { xcd_barrier_complete(bar, b.x, nloc, nx); b.st[0] = nloc; b.st[1] = nx; }
;         const unsigned old = xb_add(&bar[XB_XSUB(b.x)], 1u);
;         const unsigned gen = old / nloc;
;         if (old + 1u == (gen + 1u) * nloc) {
;             __builtin_amdgcn_fence(__ATOMIC_RELEASE, "agent");
;             asm volatile("s_waitcnt vmcnt(0)" ::: "memory");
;             const unsigned og = xb_add(&bar[XB_TOP], 1u);
;             const unsigned tg = og / nx;
;             if (og + 1u == (tg + 1u) * nx) xb_add(&bar[XB_TOPGEN], 1u);
;             else XB_SPIN(xb_ld(&bar[XB_TOPGEN]) == tg, bar);
.LBB0_820:
	v_readlane_b32 s0, v254, 13
	v_readlane_b32 s1, v254, 14
	s_and_b64 vcc, exec, s[0:1]
	s_cbranch_vccnz .LBB0_872
	s_waitcnt vmcnt(0)
	s_cmp_gt_u32 s79, 63
	s_waitcnt vmcnt(0)
	s_barrier
	s_cbranch_scc1 .LBB0_871
	v_mbcnt_lo_u32_b32 v0, -1, 0
	v_mbcnt_hi_u32_b32 v0, -1, v0
	s_nop 0
	v_cmp_eq_u32_e32 vcc, 0, v0
	s_and_saveexec_b64 s[0:1], vcc
	s_cbranch_execz .LBB0_870
	v_readlane_b32 s2, v254, 9
	s_waitcnt vmcnt(0) expcnt(0) lgkmcnt(0)
	s_nop 0
	v_mov_b32_e32 v0, s2
	ds_read_b32 v2, v0
	ds_read_b32 v3, v0 offset:4
	ds_read_b32 v4, v0 offset:8
	ds_read_b32 v5, v0 offset:12
	v_readlane_b32 s2, v254, 8
	s_lshl_b32 s2, s2, 8
	v_readlane_b32 s4, v254, 6
	v_readlane_b32 s5, v254, 7
	s_add_u32 s2, s4, s2
	s_addc_u32 s3, s5, 0
	v_mov_b32_e32 v1, 0x1000
	v_mov_b32_e32 v6, 1
	global_atomic_add v1, v6, s[2:3] offset:1024
	buffer_inv sc1
	s_waitcnt lgkmcnt(0)
	v_add_u32_e32 v6, 1, v4
	ds_write_b32 v0, v6 offset:8
	v_add_u32_e32 v4, 2, v4
	v_mul_lo_u32 v2, v2, v4
	v_mul_lo_u32 v3, v3, v4
	s_add_u32 s10, s86, 0x7400
	s_addc_u32 s11, s87, 0
	s_mov_b32 s4, 0x200000
	v_cmp_eq_u32_e32 vcc, 0, v5
	s_cbranch_vccnz .Lxb3_wait

; __device__ __forceinline__ unsigned xb_ld(unsigned* p)              { return __hip_atomic_load(p, __ATOMIC_RELAXED, __HIP_MEMORY_SCOPE_AGENT); }
; #define XB_SPIN(cond, bar) do { unsigned _sp = 0; while (cond) { __builtin_amdgcn_s_sleep(1); \
;     if ((++_sp & 255u) == 0u) { if (xb_ld(&(bar)[XB_TMO])) break; if (_sp > XB_SPIN_CAP) { atomicAdd(&(bar)[XB_TMO], 1u); break; } } } } while (0)
; __device__ __forceinline__ void xcd_barrier(const XcdBarrier& b, const int wid) {
;     ...
;             XB_SPIN(xb_ld(&bar[XB_XGEN(b.x)]) == gen, bar);
;             __builtin_amdgcn_fence(__ATOMIC_ACQUIRE, "agent");
;             asm volatile("s_waitcnt vmcnt(0)" ::: "memory");
.Lxb3_w:
	global_load_dword v6, v0, s[10:11] sc1
	s_sub_i32 s4, s4, 1
	s_waitcnt vmcnt(0)
	v_cmp_ge_u32_e32 vcc, v6, v3
	s_cbranch_vccnz .Lxb3_acq
	s_cmp_eq_u32 s4, 0
	s_cbranch_scc1 .Lxb3_acq
	s_sleep 1
	s_branch .Lxb3_w
.Lxb3_acq:
	s_waitcnt vmcnt(0)
.LBB0_870:
	s_or_b64 exec, exec, s[0:1]

; __device__ __forceinline__ unsigned xb_ld(unsigned* p)              { return __hip_atomic_load(p, __ATOMIC_RELAXED, __HIP_MEMORY_SCOPE_AGENT); }
; #define XB_SPIN(cond, bar) do { unsigned _sp = 0; while (cond) { __builtin_amdgcn_s_sleep(1); \
;     if ((++_sp & 255u) == 0u) { if (xb_ld(&(bar)[XB_TMO])) break; if (_sp > XB_SPIN_CAP) { atomicAdd(&(bar)[XB_TMO], 1u); break; } } } } while (0)
; __device__ __forceinline__ void xcd_barrier(const XcdBarrier& b, const int wid) {
;     ...
;             XB_SPIN(xb_ld(&bar[XB_XGEN(b.x)]) == gen, bar);
;             __builtin_amdgcn_fence(__ATOMIC_ACQUIRE, "agent");
;             asm volatile("s_waitcnt vmcnt(0)" ::: "memory");
.Lxb4_w:
	global_load_dword v6, v0, s[10:11] sc1
	s_sub_i32 s4, s4, 1
	s_waitcnt vmcnt(0)
	v_cmp_ge_u32_e32 vcc, v6, v3
	s_cbranch_vccnz .Lxb4_acq
	s_cmp_eq_u32 s4, 0
	s_cbranch_scc1 .Lxb4_acq
	s_sleep 1
	s_branch .Lxb4_w
.Lxb4_acq:
	s_waitcnt vmcnt(0)
.LBB0_1387:
	s_or_b64 exec, exec, s[0:1]

; __device__ __forceinline__ int lane_id_asm() { int l; asm volatile("v_mbcnt_lo_u32_b32 %0, -1, 0\n\tv_mbcnt_hi_u32_b32 %0, -1, %0" : "=v"(l)); return l; }
; __device__ __forceinline__ unsigned xb_ld(unsigned* p)              { return __hip_atomic_load(p, __ATOMIC_RELAXED, __HIP_MEMORY_SCOPE_AGENT); }
; __device__ __forceinline__ unsigned xb_add(unsigned* p, unsigned v) { return __hip_atomic_fetch_add(p, v, __ATOMIC_RELAXED, __HIP_MEMORY_SCOPE_AGENT); }
; #define XB_SPIN(cond, bar) do { unsigned _sp = 0; while (cond) { __builtin_amdgcn_s_sleep(1); \
;     if ((++_sp & 255u) == 0u) { if (xb_ld(&(bar)[XB_TMO])) break; if (_sp > XB_SPIN_CAP) { atomicAdd(&(bar)[XB_TMO], 1u); break; } } } } while (0)
; __device__ __forceinline__ void xcd_barrier(const XcdBarrier& b, const int wid) {
;     asm volatile("s_waitcnt vmcnt(0)" ::: "memory");
;     __syncthreads();
;     if (wid == 0 && lane_id_asm() == 0) {
;         unsigned* bar = b.bar;
;         __builtin_amdgcn_s_waitcnt(0);
;         unsigned nloc = b.st[0], nx = b.st[1];
;         if (nloc == 0u) { xcd_barrier_complete(bar, b.x, nloc, nx); b.st[0] = nloc; b.st[1] = nx; }
;         const unsigned old = xb_add(&bar[XB_XSUB(b.x)], 1u);
;         const unsigned gen = old / nloc;
;         if (old + 1u == (gen + 1u) * nloc) {
;             __builtin_amdgcn_fence(__ATOMIC_RELEASE, "agent");
;             asm volatile("s_waitcnt vmcnt(0)" ::: "memory");
;             const unsigned og = xb_add(&bar[XB_TOP], 1u);
;             const unsigned tg = og / nx;
;             if (og + 1u == (tg + 1u) * nx) xb_add(&bar[XB_TOPGEN], 1u);
;             else XB_SPIN(xb_ld(&bar[XB_TOPGEN]) == tg, bar);
.LBB0_1476:
	s_and_b64 vcc, exec, s[60:61]
	s_cbranch_vccnz .LBB0_1528
	s_waitcnt vmcnt(0)
	s_cmp_gt_u32 s79, 63
	s_waitcnt vmcnt(0) lgkmcnt(0)
	s_barrier
	s_cbranch_scc1 .LBB0_1527
	v_mbcnt_lo_u32_b32 v0, -1, 0
	v_mbcnt_hi_u32_b32 v0, -1, v0
	s_nop 0
	v_cmp_eq_u32_e32 vcc, 0, v0
	s_and_saveexec_b64 s[0:1], vcc
	s_cbranch_execz .LBB0_1526
	v_readlane_b32 s2, v254, 9
	s_waitcnt vmcnt(0) expcnt(0) lgkmcnt(0)
	s_nop 0
	v_mov_b32_e32 v0, s2
	ds_read_b32 v2, v0
	ds_read_b32 v3, v0 offset:4
	ds_read_b32 v4, v0 offset:8
	ds_read_b32 v5, v0 offset:12
	v_readlane_b32 s2, v254, 8
	s_lshl_b32 s2, s2, 8
	v_readlane_b32 s4, v254, 6
	v_readlane_b32 s5, v254, 7
	s_add_u32 s2, s4, s2
	s_addc_u32 s3, s5, 0
	v_mov_b32_e32 v1, 0x1000
	v_mov_b32_e32 v6, 1
	global_atomic_add v1, v6, s[2:3] offset:1024
	buffer_inv sc1
	s_waitcnt lgkmcnt(0)
	v_add_u32_e32 v6, 1, v4
	ds_write_b32 v0, v6 offset:8
	v_add_u32_e32 v4, 2, v4
	v_mul_lo_u32 v2, v2, v4
	v_mul_lo_u32 v3, v3, v4
	s_add_u32 s10, s86, 0x7400
	s_addc_u32 s11, s87, 0
	s_mov_b32 s4, 0x200000
	v_cmp_eq_u32_e32 vcc, 0, v5
	s_cbranch_vccnz .Lxb5_wait

; __device__ __forceinline__ unsigned xb_ld(unsigned* p)              { return __hip_atomic_load(p, __ATOMIC_RELAXED, __HIP_MEMORY_SCOPE_AGENT); }
; #define XB_SPIN(cond, bar) do { unsigned _sp = 0; while (cond) { __builtin_amdgcn_s_sleep(1); \
;     if ((++_sp & 255u) == 0u) { if (xb_ld(&(bar)[XB_TMO])) break; if (_sp > XB_SPIN_CAP) { atomicAdd(&(bar)[XB_TMO], 1u); break; } } } } while (0)
; __device__ __forceinline__ void xcd_barrier(const XcdBarrier& b, const int wid) {
;     ...
;             XB_SPIN(xb_ld(&bar[XB_XGEN(b.x)]) == gen, bar);
;             __builtin_amdgcn_fence(__ATOMIC_ACQUIRE, "agent");
;             asm volatile("s_waitcnt vmcnt(0)" ::: "memory");
.Lxb5_w:
	global_load_dword v6, v0, s[10:11] sc1
	s_sub_i32 s4, s4, 1
	s_waitcnt vmcnt(0)
	v_cmp_ge_u32_e32 vcc, v6, v3
	s_cbranch_vccnz .Lxb5_acq
	s_cmp_eq_u32 s4, 0
	s_cbranch_scc1 .Lxb5_acq
	s_sleep 1
	s_branch .Lxb5_w
.Lxb5_acq:
	s_waitcnt vmcnt(0)
.LBB0_1526:
	s_or_b64 exec, exec, s[0:1]

; __device__ __forceinline__ int lane_id_asm() { int l; asm volatile("v_mbcnt_lo_u32_b32 %0, -1, 0\n\tv_mbcnt_hi_u32_b32 %0, -1, %0" : "=v"(l)); return l; }
; __device__ __forceinline__ unsigned xb_ld(unsigned* p)              { return __hip_atomic_load(p, __ATOMIC_RELAXED, __HIP_MEMORY_SCOPE_AGENT); }
; __device__ __forceinline__ unsigned xb_add(unsigned* p, unsigned v) { return __hip_atomic_fetch_add(p, v, __ATOMIC_RELAXED, __HIP_MEMORY_SCOPE_AGENT); }
; #define XB_SPIN(cond, bar) do { unsigned _sp = 0; while (cond) { __builtin_amdgcn_s_sleep(1); \
;     if ((++_sp & 255u) == 0u) { if (xb_ld(&(bar)[XB_TMO])) break; if (_sp > XB_SPIN_CAP) { atomicAdd(&(bar)[XB_TMO], 1u); break; } } } } while (0)
; __device__ __forceinline__ void xcd_barrier(const XcdBarrier& b, const int wid) {
;     asm volatile("s_waitcnt vmcnt(0)" ::: "memory");
;     __syncthreads();
;     if (wid == 0 && lane_id_asm() == 0) {
;         unsigned* bar = b.bar;
;         __builtin_amdgcn_s_waitcnt(0);
;         unsigned nloc = b.st[0], nx = b.st[1];
;         if (nloc == 0u) { xcd_barrier_complete(bar, b.x, nloc, nx); b.st[0] = nloc; b.st[1] = nx; }
;         const unsigned old = xb_add(&bar[XB_XSUB(b.x)], 1u);
;         const unsigned gen = old / nloc;
;         if (old + 1u == (gen + 1u) * nloc) {
;             __builtin_amdgcn_fence(__ATOMIC_RELEASE, "agent");
;             asm volatile("s_waitcnt vmcnt(0)" ::: "memory");
;             const unsigned og = xb_add(&bar[XB_TOP], 1u);
;             const unsigned tg = og / nx;
;             if (og + 1u == (tg + 1u) * nx) xb_add(&bar[XB_TOPGEN], 1u);
;             else XB_SPIN(xb_ld(&bar[XB_TOPGEN]) == tg, bar);
.LBB0_1621:
	s_and_b64 vcc, exec, s[60:61]
	s_cbranch_vccnz .LBB0_1673
	s_waitcnt vmcnt(0)
	s_cmp_gt_u32 s79, 63
	s_waitcnt vmcnt(0)
	s_barrier
	s_cbranch_scc1 .LBB0_1672
	v_mbcnt_lo_u32_b32 v0, -1, 0
	v_mbcnt_hi_u32_b32 v0, -1, v0
	s_nop 0
	v_cmp_eq_u32_e32 vcc, 0, v0
	s_and_saveexec_b64 s[0:1], vcc
	s_cbranch_execz .LBB0_1671
	v_readlane_b32 s2, v254, 9
	s_waitcnt vmcnt(0) expcnt(0) lgkmcnt(0)
	s_nop 0
	v_mov_b32_e32 v0, s2
	ds_read_b32 v2, v0
	ds_read_b32 v3, v0 offset:4
	ds_read_b32 v4, v0 offset:8
	ds_read_b32 v5, v0 offset:12
	v_readlane_b32 s2, v254, 8
	s_lshl_b32 s2, s2, 8
	v_readlane_b32 s4, v254, 6
	v_readlane_b32 s5, v254, 7
	s_add_u32 s2, s4, s2
	s_addc_u32 s3, s5, 0
	v_mov_b32_e32 v1, 0x1000
	v_mov_b32_e32 v6, 1
	global_atomic_add v1, v6, s[2:3] offset:1024
	buffer_inv sc1
	s_waitcnt lgkmcnt(0)
	v_add_u32_e32 v6, 1, v4
	ds_write_b32 v0, v6 offset:8
	v_add_u32_e32 v4, 2, v4
	v_mul_lo_u32 v2, v2, v4
	v_mul_lo_u32 v3, v3, v4
	s_add_u32 s10, s86, 0x7400
	s_addc_u32 s11, s87, 0
	s_mov_b32 s4, 0x200000
	v_cmp_eq_u32_e32 vcc, 0, v5
	s_cbranch_vccnz .Lxb6_wait

; __device__ __forceinline__ unsigned xb_ld(unsigned* p)              { return __hip_atomic_load(p, __ATOMIC_RELAXED, __HIP_MEMORY_SCOPE_AGENT); }
; #define XB_SPIN(cond, bar) do { unsigned _sp = 0; while (cond) { __builtin_amdgcn_s_sleep(1); \
;     if ((++_sp & 255u) == 0u) { if (xb_ld(&(bar)[XB_TMO])) break; if (_sp > XB_SPIN_CAP) { atomicAdd(&(bar)[XB_TMO], 1u); break; } } } } while (0)
; __device__ __forceinline__ void xcd_barrier(const XcdBarrier& b, const int wid) {
;     ...
;             XB_SPIN(xb_ld(&bar[XB_XGEN(b.x)]) == gen, bar);
;             __builtin_amdgcn_fence(__ATOMIC_ACQUIRE, "agent");
;             asm volatile("s_waitcnt vmcnt(0)" ::: "memory");
.Lxb6_w:
	global_load_dword v6, v0, s[10:11] sc1
	s_sub_i32 s4, s4, 1
	s_waitcnt vmcnt(0)
	v_cmp_ge_u32_e32 vcc, v6, v3
	s_cbranch_vccnz .Lxb6_acq
	s_cmp_eq_u32 s4, 0
	s_cbranch_scc1 .Lxb6_acq
	s_sleep 1
	s_branch .Lxb6_w
.Lxb6_acq:
	s_waitcnt vmcnt(0)
.LBB0_1671:
	s_or_b64 exec, exec, s[0:1]

; __device__ __forceinline__ unsigned xb_ld(unsigned* p)              { return __hip_atomic_load(p, __ATOMIC_RELAXED, __HIP_MEMORY_SCOPE_AGENT); }
; #define XB_SPIN(cond, bar) do { unsigned _sp = 0; while (cond) { __builtin_amdgcn_s_sleep(1); \
;     if ((++_sp & 255u) == 0u) { if (xb_ld(&(bar)[XB_TMO])) break; if (_sp > XB_SPIN_CAP) { atomicAdd(&(bar)[XB_TMO], 1u); break; } } } } while (0)
; __device__ __forceinline__ void xcd_barrier(const XcdBarrier& b, const int wid) {
;     ...
;             XB_SPIN(xb_ld(&bar[XB_XGEN(b.x)]) == gen, bar);
;             __builtin_amdgcn_fence(__ATOMIC_ACQUIRE, "agent");
;             asm volatile("s_waitcnt vmcnt(0)" ::: "memory");
.Lxb7_w:
	global_load_dword v6, v0, s[10:11] sc1
	s_sub_i32 s4, s4, 1
	s_waitcnt vmcnt(0)
	v_cmp_ge_u32_e32 vcc, v6, v3
	s_cbranch_vccnz .Lxb7_acq
	s_cmp_eq_u32 s4, 0
	s_cbranch_scc1 .Lxb7_acq
	s_sleep 1
	s_branch .Lxb7_w
.Lxb7_acq:
	s_waitcnt vmcnt(0)
.LBB0_1766:
	s_or_b64 exec, exec, s[0:1]

; __device__ __forceinline__ unsigned xb_ld(unsigned* p)              { return __hip_atomic_load(p, __ATOMIC_RELAXED, __HIP_MEMORY_SCOPE_AGENT); }
; #define XB_SPIN(cond, bar) do { unsigned _sp = 0; while (cond) { __builtin_amdgcn_s_sleep(1); \
;     if ((++_sp & 255u) == 0u) { if (xb_ld(&(bar)[XB_TMO])) break; if (_sp > XB_SPIN_CAP) { atomicAdd(&(bar)[XB_TMO], 1u); break; } } } } while (0)
; __device__ __forceinline__ void xcd_barrier(const XcdBarrier& b, const int wid) {
;     ...
;             XB_SPIN(xb_ld(&bar[XB_XGEN(b.x)]) == gen, bar);
;             __builtin_amdgcn_fence(__ATOMIC_ACQUIRE, "agent");
;             asm volatile("s_waitcnt vmcnt(0)" ::: "memory");
.Lxb8_w:
	global_load_dword v6, v0, s[10:11] sc1
	s_sub_i32 s4, s4, 1
	s_waitcnt vmcnt(0)
	v_cmp_ge_u32_e32 vcc, v6, v3
	s_cbranch_vccnz .Lxb8_acq
	s_cmp_eq_u32 s4, 0
	s_cbranch_scc1 .Lxb8_acq
	s_sleep 1
	s_branch .Lxb8_w
.Lxb8_acq:
	s_waitcnt vmcnt(0)
.LBB0_1900:
	s_or_b64 exec, exec, s[0:1]

; __device__ __forceinline__ unsigned xb_ld(unsigned* p)              { return __hip_atomic_load(p, __ATOMIC_RELAXED, __HIP_MEMORY_SCOPE_AGENT); }
; #define XB_SPIN(cond, bar) do { unsigned _sp = 0; while (cond) { __builtin_amdgcn_s_sleep(1); \
;     if ((++_sp & 255u) == 0u) { if (xb_ld(&(bar)[XB_TMO])) break; if (_sp > XB_SPIN_CAP) { atomicAdd(&(bar)[XB_TMO], 1u); break; } } } } while (0)
; __device__ __forceinline__ void xcd_barrier(const XcdBarrier& b, const int wid) {
;     ...
;             XB_SPIN(xb_ld(&bar[XB_XGEN(b.x)]) == gen, bar);
;             __builtin_amdgcn_fence(__ATOMIC_ACQUIRE, "agent");
;             asm volatile("s_waitcnt vmcnt(0)" ::: "memory");
.Lxb9_w:
	global_load_dword v6, v0, s[10:11] sc1
	s_sub_i32 s4, s4, 1
	s_waitcnt vmcnt(0)
	v_cmp_ge_u32_e32 vcc, v6, v3
	s_cbranch_vccnz .Lxb9_acq
	s_cmp_eq_u32 s4, 0
	s_cbranch_scc1 .Lxb9_acq
	s_sleep 1
	s_branch .Lxb9_w
.Lxb9_acq:
	s_waitcnt vmcnt(0)
.LBB0_2436:
	s_or_b64 exec, exec, s[0:1]
